# attention tile loops: fewer VALU per tile (LDS read immediates, QK accumulates in place, op_sel broadcast), staging waits relaxed, barrier 1 after K/V load issue
# speedup vs baseline: 1.0225x; 1.0039x over previous
; __device__ __forceinline__ int fresh_lane() { int l; asm volatile("v_mbcnt_lo_u32_b32 %0, -1, 0\n\tv_mbcnt_hi_u32_b32 %0, -1, %0" : "=v"(l)); return l; }
; #define ATT_QLOAD(dst, U, h) do { const int tok_ = (U).rowbase + (U).r + (U).d * ((U).q0 + 32 * w + ql); const bf16* qp_ = proj + (size_t)(((U).qcol >> 6) + (h)) * ((size_t)NT_TOK * 64) + (size_t)tok_ * 64 + 8 * hh; \
;         _Pragma("unroll") for (int ks_ = 0; ks_ < 4; ++ks_) dst[ks_] = *(const bf16x8*)(qp_ + 16 * ks_); } while (0)
; #define TAB_ROW(s) ((((s) & 8) ? 16384 : 0) + (TAB_VW(s) >> 1) * 16 + (TAB_VW(s) & 1) * 8 + ((s) & 7))
; template <int MODE  >
; __device__ __forceinline__ void p2_attention(Frame& F) {
;     ...
;     for (int k = 0;; ++k) {
;         const AttU cur = att_unit(F.vcu, F.G, k);
;         if (!cur.valid) break;
;         const int lane = fresh_lane();
;         const int ql = lane & 31, hh = lane >> 5, tid = w * 64 + lane;
;         bf16x8 qc[4];
;         if (MODE == 0) ATT_QLOAD(qc, cur, 0);
;         if (TAB_P2 && MODE == 0 && TAB_VW(k) < 2048) {
;             f32x4 trow[8]; const int row = TAB_ROW(k);
;             tab_load(F, row, lane, trow);
;             __syncthreads();
;             ATT_LOADKV(cur); tab_finish(F, row, lane, trow, gl); ATT_WRITEKV(cur);
;         } else {
;             __syncthreads();
;             if (MODE < 2) { ATT_LOADKV(cur); ATT_WRITEKV(cur); }
.LBB0_232:
	v_cndmask_b32_e64 v1, 0, 1, s[0:1]
	v_cmp_ne_u32_e64 s[4:5], 1, v1
	s_andn2_b64 vcc, exec, s[0:1]
	s_mov_b64 s[0:1], -1
	v_writelane_b32 v255, s4, 35
	s_nop 1
	v_writelane_b32 v255, s5, 36
	s_cbranch_vccz .LBB0_373
	v_mbcnt_lo_u32_b32 v104, -1, 0
	v_mbcnt_hi_u32_b32 v104, -1, v104
	s_add_i32 s4, s13, s77
	v_and_b32_e32 v1, 31, v104
	v_add_u32_e32 v2, s4, v1
	s_add_i32 s33, s6, s8
	v_mul_lo_u32 v2, v2, s90
	s_ashr_i32 s5, s7, 6
	v_add_u32_e32 v98, s33, v2
	s_mul_i32 s0, s5, 0x300000
	s_mul_hi_i32 s1, s5, 0x300000
	s_add_u32 s0, s82, s0
	v_ashrrev_i32_e32 v99, 31, v98
	v_ashrrev_i32_e32 v4, 2, v104
	s_addc_u32 s1, s83, s1
	v_lshlrev_b64 v[2:3], 7, v[98:99]
	v_and_b32_e32 v100, -8, v4
	v_lshl_add_u64 v[2:3], s[0:1], 0, v[2:3]
	v_ashrrev_i32_e32 v101, 31, v100
	v_lshl_add_u64 v[2:3], v[100:101], 1, v[2:3]
	global_load_dwordx4 v[176:179], v[2:3], off
	global_load_dwordx4 v[180:183], v[2:3], off offset:32
	global_load_dwordx4 v[184:187], v[2:3], off offset:64
	global_load_dwordx4 v[188:191], v[2:3], off offset:96
	v_readlane_b32 s0, v254, 48
	v_readlane_b32 s6, v254, 32
	v_lshlrev_b32_e32 v105, 3, v104
	v_add_u32_e32 v106, s0, v104
	v_readlane_b32 s0, v254, 51
	s_lshr_b32 s0, s0, 4
	s_mul_i32 s15, s0, s6
	v_readlane_b32 s0, v254, 30
	s_add_i32 s15, s15, s0
	s_cmpk_gt_i32 s15, 0x7ff
	v_ashrrev_i32_e32 v107, 3, v106
	v_readlane_b32 s7, v254, 33
	v_readlane_b32 s1, v254, 31
	s_cbranch_scc0 .LBB0_265
	s_and_b64 s[0:1], s[2:3], exec
	s_movk_i32 s0, 0x180
	s_cselect_b32 s16, s0, 0x200
	s_movk_i32 s0, 0xff80
	s_cselect_b32 s17, 0xffffffc0, s0
	s_ashr_i32 s0, s12, 6
	s_add_i32 s17, s17, s13
	s_mul_hi_i32 s1, s0, 0x300000
	s_mul_i32 s0, s0, 0x300000
	s_add_u32 s8, s82, s0
	s_addc_u32 s9, s83, s1
	s_ashr_i32 s0, s14, 6
	s_mul_hi_i32 s1, s0, 0x300000
	s_mul_i32 s0, s0, 0x300000
	s_add_u32 s10, s82, s0
	v_add_u32_e32 v2, s17, v107
	s_addc_u32 s11, s83, s1
	v_cmp_gt_i32_e32 vcc, s16, v107
	v_cmp_lt_i32_e64 s[0:1], -1, v2
	v_lshlrev_b32_e32 v66, 3, v104
	s_and_b64 s[0:1], vcc, s[0:1]
	v_cmp_gt_i32_e32 vcc, s88, v2
	v_and_b32_e32 v67, 56, v66
	s_and_b64 s[6:7], s[0:1], vcc
	v_mov_b32_e32 v6, 0
	v_mov_b32_e32 v10, 0
	v_mov_b32_e32 v11, 0
	v_mov_b32_e32 v12, 0
	v_mov_b32_e32 v13, 0
	v_mov_b32_e32 v14, 0
	v_mov_b32_e32 v15, 0
	v_mov_b32_e32 v16, 0
	v_mov_b32_e32 v17, 0
	s_and_saveexec_b64 s[0:1], s[6:7]
	s_cbranch_execz .LBB0_236
	v_mul_lo_u32 v2, v2, s90
	v_add_u32_e32 v2, s33, v2
	v_ashrrev_i32_e32 v3, 31, v2
	v_lshlrev_b64 v[2:3], 7, v[2:3]
	v_lshl_or_b32 v2, v67, 1, v2
	v_lshl_add_u64 v[4:5], s[8:9], 0, v[2:3]
	v_lshl_add_u64 v[2:3], s[10:11], 0, v[2:3]
	global_load_dwordx4 v[10:13], v[4:5], off
	global_load_dwordx4 v[14:17], v[2:3], off

.LBB0_250:
	s_or_b64 exec, exec, s[0:1]
	s_barrier
	v_ashrrev_i32_e32 v69, 4, v106
	v_and_b32_e32 v67, 7, v104
	v_xor_b32_e32 v70, v69, v104
	v_lshlrev_b32_e32 v69, 2, v69
	v_bitop3_b32 v67, v69, v67, 4 bitop3:0x6c
	v_lshlrev_b32_e32 v68, 7, v107
	v_lshlrev_b32_e32 v70, 4, v70
	v_lshlrev_b32_e32 v67, 4, v67
	v_readlane_b32 s0, v255, 11
	v_and_b32_e32 v70, 0x70, v70
	v_add3_u32 v70, 0, v68, v70
	v_add3_u32 v71, s0, v68, v67
	v_sub_u32_e32 v67, s16, v107
	v_cmp_lt_i32_e32 vcc, 0, v67
	s_and_saveexec_b64 s[0:1], vcc
	s_cbranch_execz .LBB0_252
	s_waitcnt vmcnt(1)
	ds_write_b128 v70, v[10:13]
	s_waitcnt vmcnt(0)
	ds_write_b128 v71, v[14:17]

; template <int MODE  >
; __device__ __forceinline__ void p2_attention(Frame& F) {
;     ...
;             tab_load(F, row, lane, trow);
;             __syncthreads();
;             ATT_LOADKV(cur); tab_finish(F, row, lane, trow, gl); ATT_WRITEKV(cur);
.Lpf_top_done:
	v_add_co_u32_e32 v2, vcc, s0, v2
	s_and_b64 s[0:1], s[2:3], exec
	s_nop 0
	v_addc_co_u32_e32 v3, vcc, 0, v3, vcc
	s_movk_i32 s0, 0x180
	s_cselect_b32 s17, s0, 0x200
	s_movk_i32 s0, 0xff80
	v_writelane_b32 v254, s21, 50
	s_cselect_b32 s20, 0xffffffc0, s0
	s_ashr_i32 s0, s12, 6
	s_add_i32 s20, s20, s13
	s_mul_hi_i32 s1, s0, 0x300000
	s_mul_i32 s0, s0, 0x300000
	s_add_u32 s12, s82, s0
	s_addc_u32 s13, s83, s1
	s_ashr_i32 s0, s14, 6
	s_mul_hi_i32 s1, s0, 0x300000
	s_mul_i32 s0, s0, 0x300000
	s_add_u32 s14, s82, s0
	v_add_u32_e32 v2, s20, v107
	s_addc_u32 s15, s83, s1
	v_cmp_gt_i32_e32 vcc, s17, v107
	v_cmp_lt_i32_e64 s[0:1], -1, v2
	s_and_b64 s[0:1], vcc, s[0:1]
	v_cmp_gt_i32_e32 vcc, s88, v2
	v_and_b32_e32 v103, 56, v105
	s_and_b64 s[8:9], s[0:1], vcc
	v_mov_b32_e32 v6, 0
	v_mov_b32_e32 v10, 0
	v_mov_b32_e32 v11, 0
	v_mov_b32_e32 v12, 0
	v_mov_b32_e32 v13, 0
	v_mov_b32_e32 v14, 0
	v_mov_b32_e32 v15, 0
	v_mov_b32_e32 v16, 0
	v_mov_b32_e32 v17, 0
	s_waitcnt lgkmcnt(0)
	s_and_saveexec_b64 s[0:1], s[8:9]
	s_cbranch_execz .LBB0_268
	v_mul_lo_u32 v2, v2, s90
	v_add_u32_e32 v2, s33, v2
	v_ashrrev_i32_e32 v3, 31, v2
	v_lshlrev_b64 v[2:3], 7, v[2:3]
	v_lshl_or_b32 v2, v103, 1, v2
	v_lshl_add_u64 v[4:5], s[12:13], 0, v[2:3]
	v_lshl_add_u64 v[2:3], s[14:15], 0, v[2:3]
	global_load_dwordx4 v[10:13], v[4:5], off
	global_load_dwordx4 v[14:17], v[2:3], off

; template <int MODE  >
; __device__ __forceinline__ void p2_attention(Frame& F) {
;     ...
;             __syncthreads();
;             ATT_LOADKV(cur); tab_finish(F, row, lane, trow, gl); ATT_WRITEKV(cur);
.LBB0_282:
	s_or_b64 exec, exec, s[0:1]
	s_barrier
	v_readlane_b32 s98, v254, 51
	s_nop 3
	s_cmp_gt_u32 s98, 3
	s_cbranch_scc1 .Lpf_nowait
	s_waitcnt vmcnt(0)

; #define LAS __attribute__((address_space(3)))
;     constexpr int NTILE = 1 + 2 * HALFW / 32, JM = HALFW / 32;
;     const int ql = lane & 31, hh = lane >> 5;
;     o0 = (f32x16){}; o1 = (f32x16){};
;     float m = -1e30f, lsum = 0.f;
;     const int i15 = lane & 15, G = (lane >> 4) & 1, ql4 = ql - 4 * hh;
;     f32x16 CL, CM, CR;
;     { const float sq = slope2 * (float)ql;
; #pragma unroll
;       for (int reg = 0; reg < 16; ++reg) { const float kb_ = slope2 * (float)((reg & 3) + 8 * (reg >> 2) + 4 * hh); CL[reg] = kb_; CR[reg] = -kb_; CM[reg] = -fabsf(kb_ - sq); } }
;     const LAS unsigned char* kb = Ks + (LDSFLAT ? 0 : (32 * w + ql) * 128); const int sw = LDSFLAT ? 0 : ((ql >> 1) & 7);
;     int koff[4];
; #pragma unroll
;     for (int ks = 0; ks < 4; ++ks) koff[ks] = LDSFLAT ? 0 : (((2 * ks + hh) ^ sw) << 4);
;     const int c0 = (2 * G + ((i15 & 3) >> 1)) ^ (((i15 >> 3) & 1) << 2);
;     const LAS unsigned char* vb0 = LDSFLAT ? Vs : Vs + (32 * w + 4 * hh + (i15 >> 2)) * 128 + (i15 & 1) * 8 + (c0 << 4);
;     const LAS unsigned char* vb1 = LDSFLAT ? Vs + 64 : Vs + (32 * w + 4 * hh + (i15 >> 2)) * 128 + (i15 & 1) * 8 + ((c0 ^ 4) << 4);
;     bf16x8 kf[4];
; #pragma unroll
;     for (int ks = 0; ks < 4; ++ks) kf[ks] = *(const LAS bf16x8*)(kb + koff[ks]);
; template <int MODE  >
; __device__ __forceinline__ void p2_attention(Frame& F) {
;     ...
;                 const float slope = exp2f(-0.25f * (float)(2 * cur.head + 1));
;                 att_wave<64, MODE == 6>(ln, w, Ks, Vs, cur.q0 - 64 + 32 * w, cur.Lsub, qc, slope * (float)cur.d * LOG2E, o0, o1, m, l, MODE == 5 ? 2 : 0, MODE == 5 ? 3 : 5);
.LBB0_306:
	s_or_b64 exec, exec, s[6:7]
	s_waitcnt vmcnt(3)
	v_lshlrev_b64 v[2:3], 6, v[98:99]
	v_lshl_add_u64 v[2:3], v[2:3], 1, s[82:83]
	v_lshl_add_u64 v[2:3], v[100:101], 1, v[2:3]
	s_add_i32 s5, s5, 1
	v_mov_b32_e32 v4, 0x300000
	s_xor_b64 s[42:43], s[2:3], -1
	v_mad_i64_i32 v[212:213], s[2:3], s5, v4, v[2:3]
	s_lshl_b32 s2, s40, 1
	s_or_b32 s2, s2, 1
	v_cvt_f32_i32_e32 v7, s2
	v_ashrrev_i32_e32 v2, 5, v104
	v_lshlrev_b32_e32 v3, 2, v2
	v_or_b32_e32 v5, 2, v3
	v_cvt_f32_i32_e32 v216, v5
	v_add_u32_e32 v5, 9, v3
	v_mul_f32_e32 v8, 0xbe800000, v7
	s_mov_b32 s2, 0xc2fc0000
	v_cvt_f32_i32_e32 v219, v5
	v_add_u32_e32 v5, 11, v3
	v_cmp_gt_f32_e32 vcc, s2, v8
	v_mov_b32_e32 v8, 0x42800000
	v_cvt_f32_i32_e32 v221, v5
	v_add_u32_e32 v5, 17, v3
	v_cndmask_b32_e32 v8, 0, v8, vcc
	v_or_b32_e32 v4, 1, v3
	v_cvt_f32_i32_e32 v223, v5
	v_add_u32_e32 v5, 19, v3
	v_fmac_f32_e32 v8, 0xbe800000, v7
	v_cvt_f32_i32_e32 v215, v4
	v_or_b32_e32 v4, 3, v3
	v_cvt_f32_i32_e32 v225, v5
	v_add_u32_e32 v5, 25, v3
	v_exp_f32_e32 v7, v8
	s_and_b64 s[2:3], vcc, exec
	v_cvt_f32_i32_e32 v217, v4
	v_add_u32_e32 v4, 8, v3
	v_cvt_f32_i32_e32 v227, v5
	v_add_u32_e32 v5, 27, v3
	v_cvt_f32_i32_e32 v8, s90
	s_mul_i32 s3, s58, 0x3000000
	v_cvt_f32_i32_e32 v218, v4
	v_add_u32_e32 v4, 10, v3
	v_cvt_f32_i32_e32 v229, v5
	v_lshrrev_b32_e32 v5, 1, v104
	s_cselect_b32 s62, 0xffffffc0, 0
	s_mul_hi_i32 s2, s58, 0x3000000
	s_add_u32 s59, s72, s3
	v_cvt_f32_i32_e32 v220, v4
	v_add_u32_e32 v4, 16, v3
	v_bitop3_b32 v6, v5, v2, 7 bitop3:0x6c
	s_addc_u32 s60, s73, s2
	s_lshl_b32 s2, s40, 6
	v_cvt_f32_i32_e32 v222, v4
	v_add_u32_e32 v4, 18, v3
	v_lshlrev_b32_e32 v237, 4, v6
	v_add_u32_e32 v6, 2, v2
	s_ashr_i32 s3, s2, 31
	v_ldexp_f32 v7, v7, s62
	v_cvt_f32_i32_e32 v224, v4
	v_add_u32_e32 v4, 24, v3
	v_bitop3_b32 v6, v6, v5, 7 bitop3:0x78
	s_lshl_b64 s[2:3], s[2:3], 1
	v_mul_f32_e32 v7, v7, v8
	v_cvt_f32_i32_e32 v226, v4
	v_add_u32_e32 v4, 26, v3
	v_lshlrev_b32_e32 v238, 4, v6
	v_add_u32_e32 v6, 4, v2
	v_add_u32_e32 v2, 6, v2
	s_add_u32 s2, s59, s2
	v_mul_f32_e32 v230, 0x3fb8aa3b, v7
	v_cvt_f32_ubyte0_e32 v236, v1
	v_cvt_f32_i32_e32 v228, v4
	v_or_b32_e32 v4, s77, v1
	v_bitop3_b32 v2, v2, v5, 7 bitop3:0x78
	s_addc_u32 s3, s60, s3
	s_waitcnt vmcnt(3)
	v_pk_mul_f32 v[18:19], v[230:231], v[216:217] op_sel_hi:[0,1]
	v_lshlrev_b32_e32 v240, 4, v2
	v_lshl_add_u32 v241, v4, 7, 0
	v_lshrrev_b32_e32 v2, 3, v104
	v_and_b32_e32 v4, 5, v5
	v_writelane_b32 v255, s2, 37
	v_fma_f32 v7, -v230, v236, v18
	v_cvt_f32_i32_e32 v214, v3
	v_bitop3_b32 v6, v6, v5, 7 bitop3:0x78
	v_and_or_b32 v2, v2, 2, v4
	v_bfe_u32 v5, v104, 2, 2
	v_writelane_b32 v255, s3, 38
	s_mul_hi_i32 s2, s58, 0x180000
	s_mul_i32 s58, s58, 0x180000
	v_readlane_b32 s3, v254, 55
	v_and_b32_e32 v48, 0x7fffffff, v7
	v_add_u32_e32 v7, s77, v3
	v_lshlrev_b32_e32 v2, 4, v2
	s_add_u32 s58, s3, s58
	v_readlane_b32 s3, v254, 57
	v_add_lshl_u32 v5, v7, v5, 7
	s_addc_u32 s59, s3, s2
	s_mov_b32 s2, s40
	v_bitop3_b32 v2, v2, v5, 64 bitop3:0xde
	s_ashr_i32 s41, s40, 31
	v_writelane_b32 v255, s2, 39
	v_add_u32_e32 v234, 0, v2
	v_lshlrev_b32_e32 v2, 1, v104
	v_writelane_b32 v255, s3, 40
	s_lshl_b64 s[2:3], s[40:41], 2
	v_pk_mul_f32 v[16:17], v[230:231], v[214:215] op_sel_hi:[0,1]
	v_pk_mul_f32 v[20:21], v[230:231], v[218:219] op_sel_hi:[0,1]
	v_pk_mul_f32 v[22:23], v[230:231], v[220:221] op_sel_hi:[0,1]
	v_pk_mul_f32 v[24:25], v[230:231], v[222:223] op_sel_hi:[0,1]
	v_pk_mul_f32 v[26:27], v[230:231], v[224:225] op_sel_hi:[0,1]
	v_pk_mul_f32 v[28:29], v[230:231], v[226:227] op_sel_hi:[0,1]
	v_pk_mul_f32 v[30:31], v[230:231], v[228:229] op_sel_hi:[0,1]
	v_and_b32_e32 v2, 32, v2
	v_lshlrev_b32_e32 v4, 4, v4
	v_lshlrev_b32_e32 v239, 4, v6
	v_sub_u32_e32 v6, v1, v3
	s_add_u32 s2, s58, s2
	v_fma_f32 v8, -v230, v236, v19
	v_fma_f32 v9, -v230, v236, v16
	v_fma_f32 v10, -v230, v236, v17
	v_fma_f32 v11, -v230, v236, v20
	v_fma_f32 v12, -v230, v236, v21
	v_fma_f32 v13, -v230, v236, v22
	v_fma_f32 v14, -v230, v236, v23
	v_fma_f32 v15, -v230, v236, v24
	v_fma_f32 v56, -v230, v236, v25
	v_fma_f32 v54, -v230, v236, v26
	v_fma_f32 v55, -v230, v236, v27
	v_fma_f32 v52, -v230, v236, v28
	v_fma_f32 v53, -v230, v236, v29
	v_fma_f32 v32, -v230, v236, v30
	v_fma_f32 v33, -v230, v236, v31
	v_or3_b32 v2, v5, v2, v4
	v_and_b32_e32 v242, 8, v66
	s_mov_b32 s5, 0
	v_cmp_gt_i32_e64 s[6:7], 0, v6
	v_cmp_gt_i32_e64 s[8:9], 1, v6
	v_cmp_gt_i32_e64 s[10:11], 2, v6
	v_cmp_gt_i32_e64 s[12:13], 3, v6
	v_cmp_gt_i32_e64 s[14:15], 8, v6
	v_cmp_gt_i32_e64 s[16:17], 9, v6
	v_cmp_gt_i32_e64 s[18:19], 10, v6
	v_cmp_gt_i32_e64 s[20:21], 11, v6
	v_cmp_gt_i32_e64 s[22:23], 16, v6
	v_cmp_gt_i32_e64 s[24:25], 17, v6
	v_cmp_gt_i32_e64 s[26:27], 18, v6
	v_cmp_gt_i32_e64 s[28:29], 19, v6
	v_cmp_gt_i32_e64 s[30:31], 24, v6
	v_cmp_gt_i32_e64 s[34:35], 25, v6
	v_cmp_gt_i32_e64 s[36:37], 26, v6
	v_cmp_gt_i32_e64 s[38:39], 27, v6
	v_cmp_lt_i32_e64 s[96:97], 0, v6
	v_cmp_lt_i32_e64 s[44:45], 1, v6
	v_cmp_lt_i32_e64 s[46:47], 2, v6
	v_cmp_lt_i32_e64 s[82:83], 3, v6
	v_cmp_lt_i32_e64 s[84:85], 8, v6
	v_cmp_lt_i32_e64 s[78:79], 9, v6
	v_cmp_lt_i32_e64 s[86:87], 10, v6
	v_cmp_lt_i32_e64 s[0:1], 11, v6
	v_cmp_lt_i32_e64 s[56:57], 16, v6
	s_addc_u32 s3, s59, s3
	v_cmp_lt_i32_e64 s[58:59], 17, v6
	v_cmp_lt_i32_e64 s[60:61], 18, v6
	v_xor_b32_e32 v34, 0x80000000, v18
	v_xor_b32_e32 v35, 0x80000000, v19
	v_xor_b32_e32 v36, 0x80000000, v20
	v_xor_b32_e32 v37, 0x80000000, v21
	v_xor_b32_e32 v38, 0x80000000, v22
	v_xor_b32_e32 v39, 0x80000000, v23
	v_xor_b32_e32 v40, 0x80000000, v24
	v_xor_b32_e32 v41, 0x80000000, v25
	v_xor_b32_e32 v42, 0x80000000, v26
	v_xor_b32_e32 v43, 0x80000000, v27
	v_xor_b32_e32 v44, 0x80000000, v28
	v_xor_b32_e32 v45, 0x80000000, v29
	v_xor_b32_e32 v46, 0x80000000, v30
	v_xor_b32_e32 v47, 0x80000000, v31
	v_and_b32_e32 v49, 0x7fffffff, v8
	v_and_b32_e32 v51, 0x7fffffff, v33
	v_and_b32_e32 v50, 0x7fffffff, v32
	v_xor_b32_e32 v33, 0x80000000, v17
	v_xor_b32_e32 v32, 0x80000000, v16
	v_add_u32_e32 v233, 0, v2
	v_sub_u32_e32 v245, 0xffffff80, v1
	v_add_u32_e32 v246, s4, v3
	v_sub_u32_e32 v247, 0xffffffc0, v1
	v_and_b32_e32 v53, 0x7fffffff, v53
	v_and_b32_e32 v52, 0x7fffffff, v52
	v_and_b32_e32 v55, 0x7fffffff, v55
	v_and_b32_e32 v54, 0x7fffffff, v54
	v_and_b32_e32 v57, 0x7fffffff, v56
	v_cmp_lt_i32_e64 s[62:63], 19, v6
	v_cmp_lt_i32_e64 s[64:65], 24, v6
	v_cmp_lt_i32_e64 s[66:67], 25, v6
	v_cmp_lt_i32_e64 s[68:69], 26, v6
	v_and_b32_e32 v56, 0x7fffffff, v15
	v_and_b32_e32 v59, 0x7fffffff, v14
	v_cmp_lt_i32_e64 s[70:71], 27, v6
	v_and_b32_e32 v58, 0x7fffffff, v13
	v_and_b32_e32 v61, 0x7fffffff, v12
	v_and_b32_e32 v60, 0x7fffffff, v11
	v_and_b32_e32 v63, 0x7fffffff, v10
	v_and_b32_e32 v62, 0x7fffffff, v9
	s_waitcnt lgkmcnt(0)
	s_barrier
; __device__ __forceinline__ void tab_load(const Frame& F, int row, int lane, f32x4 (&t)[8]) {
;     const float* s0 = (row < 16384 ? F.expert_u + (size_t)row * DM : F.expert_v + (size_t)(row - 16384) * DM) + 16 * lane;
; #pragma unroll
;     for (int q = 0; q < 8; ++q) t[q] = *(const f32x4*)(s0 + 1024 * (q >> 2) + 4 * (q & 3));
; }
	v_readlane_b32 s98, v254, 51
	v_readlane_b32 s99, v254, 30
	v_readlane_b32 s100, v254, 53
	s_nop 3
	s_cmp_lt_u32 s98, 3
	s_cbranch_scc1 .Lpf_done
	s_add_i32 s98, s98, 1
	s_lshl_b32 s99, s99, 3
	s_and_b32 s99, s99, -16
	s_or_b32 s99, s99, s100
	s_and_b32 s100, s98, 7
	s_or_b32 s99, s99, s100
	s_lshl_b32 s99, s99, 13
	v_mbcnt_lo_u32_b32 v192, -1, 0
	v_mbcnt_hi_u32_b32 v192, -1, v192
	v_lshlrev_b32_e32 v192, 6, v192
	s_cmp_lt_u32 s98, 16
	s_cbranch_scc1 .Lpf_real
	s_mov_b32 s99, 0
	v_mov_b32_e32 v192, 0
	s_mov_b32 s98, 0

; #define LAS __attribute__((address_space(3)))
;     ...
;             s16x4 vlo[2][2], vhi[2][2];
; #pragma unroll
;             for (int st = 0; st < 2; ++st) {
;                 vlo[0][st] = __builtin_bit_cast(s16x4, __builtin_amdgcn_ds_read_tr16_b64_v4i16((LAS s16x4*)(vb0 + 4096 * j + 2048 * st)));
;                 vhi[0][st] = __builtin_bit_cast(s16x4, __builtin_amdgcn_ds_read_tr16_b64_v4i16((LAS s16x4*)(vb0 + 4096 * j + 2048 * st + 1024)));
;                 vlo[1][st] = __builtin_bit_cast(s16x4, __builtin_amdgcn_ds_read_tr16_b64_v4i16((LAS s16x4*)(vb1 + 4096 * j + 2048 * st)));
;                 vhi[1][st] = __builtin_bit_cast(s16x4, __builtin_amdgcn_ds_read_tr16_b64_v4i16((LAS s16x4*)(vb1 + 4096 * j + 2048 * st + 1024))); }
;             f32x16 s; float cj;
;             const float cl = slope2 * (float)(32 * j - HALFW - ql);
;             if (j < JM) { s = __builtin_amdgcn_mfma_f32_32x32x16_bf16(kf[0], qf[0], CL, 0, 0, 0); cj = cl; }
;             else if (j == JM) { s = __builtin_amdgcn_mfma_f32_32x32x16_bf16(kf[0], qf[0], CM, 0, 0, 0); cj = 0.f; }
;             else { s = __builtin_amdgcn_mfma_f32_32x32x16_bf16(kf[0], qf[0], CR, 0, 0, 0); cj = -cl; }
.LBB0_315:
	s_andn2_b64 vcc, exec, s[76:77]
	s_cbranch_vccnz .LBB0_337
	s_waitcnt lgkmcnt(3)
	v_add_u32_e32 v1, v244, v242
	v_add_u32_e32 v4, v243, v242
	v_add_u32_e32 v1, 0x10000, v1
	v_add_u32_e32 v4, 0x10000, v4
	ds_read_b64_tr_b16 v[208:209], v1
	ds_read_b64_tr_b16 v[210:211], v1 offset:1024
	s_waitcnt lgkmcnt(3)
	ds_read_b64_tr_b16 v[10:11], v4
	ds_read_b64_tr_b16 v[12:13], v4 offset:1024
	ds_read_b64_tr_b16 v[6:7], v1 offset:2048
	ds_read_b64_tr_b16 v[8:9], v1 offset:3072
	v_add_u32_e32 v2, s91, v245
	v_cvt_f32_i32_e32 v15, v2
	ds_read_b64_tr_b16 v[2:3], v4 offset:2048
	ds_read_b64_tr_b16 v[4:5], v4 offset:3072
	s_cmp_gt_u32 s93, 3
	s_mov_b64 s[76:77], -1
	v_mul_f32_e32 v15, v232, v15
	s_cbranch_scc0 .LBB0_322
	s_cmpk_lg_i32 s91, 0x80
	s_cbranch_scc0 .LBB0_319
	v_xor_b32_e32 v1, 0x80000000, v15
	s_mov_b64 s[76:77], 0
	s_waitcnt vmcnt(3)
	v_mfma_f32_32x32x16_bf16 v[144:159], v[204:207], v[176:179], v[112:127]
.LBB0_319:
	s_andn2_b64 vcc, exec, s[76:77]
	s_cbranch_vccnz .LBB0_321
	s_nop 9
	v_xor_b32_e32 v159, 0x80000000, v129
	v_xor_b32_e32 v158, 0x80000000, v128
	v_xor_b32_e32 v157, 0x80000000, v131
	v_xor_b32_e32 v156, 0x80000000, v130
	v_xor_b32_e32 v155, 0x80000000, v133
	v_xor_b32_e32 v154, 0x80000000, v132
	v_xor_b32_e32 v153, 0x80000000, v135
	v_xor_b32_e32 v152, 0x80000000, v134
	v_xor_b32_e32 v151, 0x80000000, v137
	v_xor_b32_e32 v150, 0x80000000, v136
	v_xor_b32_e32 v149, 0x80000000, v139
	v_xor_b32_e32 v148, 0x80000000, v138
	v_xor_b32_e32 v147, 0x80000000, v141
	v_xor_b32_e32 v146, 0x80000000, v140
	v_xor_b32_e32 v145, 0x80000000, v143
	v_xor_b32_e32 v144, 0x80000000, v142
	v_mov_b32_e32 v1, 0
	s_waitcnt vmcnt(3)
	v_mfma_f32_32x32x16_bf16 v[144:159], v[204:207], v[176:179], v[144:159]

; #define LAS __attribute__((address_space(3)))
;     ...
;             if (j < JM) { s = __builtin_amdgcn_mfma_f32_32x32x16_bf16(kf[0], qf[0], CL, 0, 0, 0); cj = cl; }
;             else if (j == JM) { s = __builtin_amdgcn_mfma_f32_32x32x16_bf16(kf[0], qf[0], CM, 0, 0, 0); cj = 0.f; }
;             else { s = __builtin_amdgcn_mfma_f32_32x32x16_bf16(kf[0], qf[0], CR, 0, 0, 0); cj = -cl; }
; #pragma unroll
;             for (int ks = 1; ks < 4; ++ks) s = __builtin_amdgcn_mfma_f32_32x32x16_bf16(kf[ks], qf[ks], s, 0, 0, 0);
; #pragma unroll
;             for (int ks = 0; ks < 4; ++ks) kf[ks] = *(const LAS bf16x8*)(kb + 4096 * jn + koff[ks]);
;             if (j == 0) {
; #pragma unroll
;                 for (int reg = 0; reg < 16; ++reg) s[reg] = ((reg & 3) + 8 * (reg >> 2) >= ql4) ? s[reg] : -INFINITY;
;             } else if (j == NTILE - 1) {
; #pragma unroll
;                 for (int reg = 0; reg < 16; ++reg) s[reg] = ((reg & 3) + 8 * (reg >> 2) <= ql4) ? s[reg] : -INFINITY;
.LBB0_322:
	s_andn2_b64 vcc, exec, s[76:77]
	s_cbranch_vccnz .LBB0_324
	s_waitcnt vmcnt(3)
	v_mfma_f32_32x32x16_bf16 v[144:159], v[204:207], v[176:179], v[96:111]
	v_mov_b32_e32 v1, v15
.LBB0_324:
	s_waitcnt vmcnt(2)
	v_mfma_f32_32x32x16_bf16 v[144:159], v[200:203], v[180:183], v[144:159]
	v_add_u32_e32 v15, v14, v237
	s_waitcnt lgkmcnt(8)
	v_add_u32_e32 v160, v14, v238
	ds_read_b128 v[204:207], v15
	ds_read_b128 v[200:203], v160
	v_add_u32_e32 v15, v14, v239
	v_add_u32_e32 v14, v14, v240
	s_cmp_lt_i32 s93, 8
	s_mov_b64 s[76:77], -1
	s_waitcnt vmcnt(1)
	v_mfma_f32_32x32x16_bf16 v[144:159], v[196:199], v[184:187], v[144:159]
	s_waitcnt vmcnt(0)
	v_mfma_f32_32x32x16_bf16 v[144:159], v[192:195], v[188:191], v[144:159]
	ds_read_b128 v[196:199], v15
	ds_read_b128 v[192:195], v14
	s_cbranch_scc1 .LBB0_328
	s_nop 8
	s_cmp_eq_u32 s93, 8
	s_cbranch_scc0 .LBB0_327
	v_cndmask_b32_e64 v144, v144, v235, s[6:7]
	v_cndmask_b32_e64 v145, v145, v235, s[8:9]
	v_cndmask_b32_e64 v146, v146, v235, s[10:11]
	v_cndmask_b32_e64 v147, v147, v235, s[12:13]
	v_cndmask_b32_e64 v148, v148, v235, s[14:15]
	v_cndmask_b32_e64 v149, v149, v235, s[16:17]
	v_cndmask_b32_e64 v150, v150, v235, s[18:19]
	v_cndmask_b32_e64 v151, v151, v235, s[20:21]
	v_cndmask_b32_e64 v152, v152, v235, s[22:23]
	v_cndmask_b32_e64 v153, v153, v235, s[24:25]
	v_cndmask_b32_e64 v154, v154, v235, s[26:27]
	v_cndmask_b32_e64 v155, v155, v235, s[28:29]
	v_cndmask_b32_e64 v156, v156, v235, s[30:31]
	v_cndmask_b32_e64 v157, v157, v235, s[34:35]
	v_cndmask_b32_e64 v158, v158, v235, s[36:37]
	v_cndmask_b32_e64 v159, v159, v235, s[38:39]

;     ...
;                 for (int reg = 0; reg < 16; ++reg) s[reg] = ((reg & 3) + 8 * (reg >> 2) >= ql4) ? s[reg] : -INFINITY;
;             } else if (j == NTILE - 1) {
; #pragma unroll
;                 for (int reg = 0; reg < 16; ++reg) s[reg] = ((reg & 3) + 8 * (reg >> 2) <= ql4) ? s[reg] : -INFINITY;
;             }
;             if (kt0 < 0 || kt0 + 31 >= Lsub) {
;                 const int kq = kt0 + 4 * hh;
; #pragma unroll
;                 for (int reg = 0; reg < 16; ++reg) { const int kpos = kq + (reg & 3) + 8 * (reg >> 2); s[reg] = ((unsigned)kpos < (unsigned)Lsub) ? s[reg] : -INFINITY; }
;             }
;             float tmax = fmaxf(fmaxf(s[0], s[1]), s[2]);
; #pragma unroll
;             for (int reg = 3; reg < 15; reg += 2) tmax = fmaxf(fmaxf(tmax, s[reg]), s[reg + 1]);
;             tmax = fmaxf(tmax, s[15]) + cj;
;             tmax = fmaxf(tmax, __shfl_xor(tmax, 32));
;             if (__any(tmax > m + 8.0f)) { const float mnew = fmaxf(m, tmax); const float alpha = __builtin_amdgcn_exp2f(m - mnew); lsum *= alpha; m = mnew;
; #pragma unroll
;                 for (int reg = 0; reg < 16; ++reg) { o0[reg] *= alpha; o1[reg] *= alpha; } }
;             const float dd = cj - m;
;             f32x2 ps2 = {0.f, 0.f}; const f32x2 dd2 = {dd, dd};
; #pragma unroll
;             for (int rp = 0; rp < 8; ++rp) { f32x2 t; { const f32x2 in_ = {s[2 * rp], s[2 * rp + 1]}; asm("v_pk_add_f32 %0, %1, %2" : "=v"(t) : "v"(in_), "v"(dd2)); } t[0] = __builtin_amdgcn_exp2f(t[0]); t[1] = __builtin_amdgcn_exp2f(t[1]); s[2 * rp] = t[0]; s[2 * rp + 1] = t[1]; asm("v_pk_add_f32 %0, %1, %2" : "=v"(ps2) : "v"(ps2), "v"(t)); }
;             lsum += ps2[0] + ps2[1];
;             bf16x8 pf[2];
; #pragma unroll
;             for (int st = 0; st < 2; ++st) { v4u t; t.x = pk2(s[8 * st + 0], s[8 * st + 1]); t.y = pk2(s[8 * st + 2], s[8 * st + 3]); t.z = pk2(s[8 * st + 4], s[8 * st + 5]); t.w = pk2(s[8 * st + 6], s[8 * st + 7]); pf[st] = __builtin_bit_cast(bf16x8, t); }
; #pragma unroll
;             for (int st = 0; st < 2; ++st) {
;                 const bf16x8 v0 = (bf16x8){vlo[0][st][0], vlo[0][st][1], vlo[0][st][2], vlo[0][st][3], vhi[0][st][0], vhi[0][st][1], vhi[0][st][2], vhi[0][st][3]};
;                 const bf16x8 v1 = (bf16x8){vlo[1][st][0], vlo[1][st][1], vlo[1][st][2], vlo[1][st][3], vhi[1][st][0], vhi[1][st][1], vhi[1][st][2], vhi[1][st][3]};
.LBB0_328:
	s_andn2_b64 vcc, exec, s[76:77]
	s_cbranch_vccnz .LBB0_332
	s_cmp_eq_u32 s93, 0
	s_cbranch_scc0 .LBB0_331
	s_nop 4
	v_cndmask_b32_e64 v144, v144, v235, s[96:97]
	v_cndmask_b32_e64 v145, v145, v235, s[44:45]
	v_cndmask_b32_e64 v146, v146, v235, s[46:47]
	v_cndmask_b32_e64 v147, v147, v235, s[82:83]
	v_cndmask_b32_e64 v148, v148, v235, s[84:85]
	v_cndmask_b32_e64 v149, v149, v235, s[78:79]
	v_cndmask_b32_e64 v150, v150, v235, s[86:87]
	v_cndmask_b32_e64 v151, v151, v235, s[0:1]
	v_cndmask_b32_e64 v152, v152, v235, s[56:57]
	v_cndmask_b32_e64 v153, v153, v235, s[58:59]
	v_cndmask_b32_e64 v154, v154, v235, s[60:61]
	v_cndmask_b32_e64 v155, v155, v235, s[62:63]
	v_cndmask_b32_e64 v156, v156, v235, s[64:65]
	v_cndmask_b32_e64 v157, v157, v235, s[66:67]
	v_cndmask_b32_e64 v158, v158, v235, s[68:69]
	v_cndmask_b32_e64 v159, v159, v235, s[70:71]
.LBB0_331:
	s_nop 4
.LBB0_332:
	s_add_i32 s74, s72, 0xffffff9f
	s_cmp_gt_i32 s95, -1
	s_cselect_b64 s[72:73], -1, 0
	s_cmp_lt_i32 s74, s88
	s_cselect_b64 s[74:75], -1, 0
	s_and_b64 s[72:73], s[72:73], s[74:75]
	s_and_b64 vcc, exec, s[72:73]
	s_cbranch_vccnz .LBB0_334
	v_add_u32_e32 v14, s91, v246
	v_add_u32_e32 v15, 0xffffff80, v14
	v_cmp_gt_u32_e32 vcc, s88, v15
	v_add_u32_e32 v15, 0xffffff81, v14
	s_nop 0
	v_cndmask_b32_e32 v144, v235, v144, vcc
	v_cmp_gt_u32_e32 vcc, s88, v15
	v_add_u32_e32 v15, 0xffffff82, v14
	s_nop 0
	v_cndmask_b32_e32 v145, v235, v145, vcc
	v_cmp_gt_u32_e32 vcc, s88, v15
	v_add_u32_e32 v15, 0xffffff83, v14
	s_nop 0
	v_cndmask_b32_e32 v146, v235, v146, vcc
	v_cmp_gt_u32_e32 vcc, s88, v15
	v_add_u32_e32 v15, 0xffffff88, v14
	s_nop 0
	v_cndmask_b32_e32 v147, v235, v147, vcc
	v_cmp_gt_u32_e32 vcc, s88, v15
	v_add_u32_e32 v15, 0xffffff89, v14
	s_nop 0
	v_cndmask_b32_e32 v148, v235, v148, vcc
	v_cmp_gt_u32_e32 vcc, s88, v15
	v_add_u32_e32 v15, 0xffffff8a, v14
	s_nop 0
	v_cndmask_b32_e32 v149, v235, v149, vcc
	v_cmp_gt_u32_e32 vcc, s88, v15
	v_add_u32_e32 v15, 0xffffff8b, v14
	s_nop 0
	v_cndmask_b32_e32 v150, v235, v150, vcc
	v_cmp_gt_u32_e32 vcc, s88, v15
	v_add_u32_e32 v15, 0xffffff90, v14
	s_nop 0
	v_cndmask_b32_e32 v151, v235, v151, vcc
	v_cmp_gt_u32_e32 vcc, s88, v15
	v_add_u32_e32 v15, 0xffffff91, v14
	s_nop 0
	v_cndmask_b32_e32 v152, v235, v152, vcc
	v_cmp_gt_u32_e32 vcc, s88, v15
	v_add_u32_e32 v15, 0xffffff92, v14
	s_nop 0
	v_cndmask_b32_e32 v153, v235, v153, vcc
	v_cmp_gt_u32_e32 vcc, s88, v15
	v_add_u32_e32 v15, 0xffffff93, v14
	s_nop 0
	v_cndmask_b32_e32 v154, v235, v154, vcc
	v_cmp_gt_u32_e32 vcc, s88, v15
	v_add_u32_e32 v15, 0xffffff98, v14
	s_nop 0
	v_cndmask_b32_e32 v155, v235, v155, vcc
	v_cmp_gt_u32_e32 vcc, s88, v15
	v_add_u32_e32 v15, 0xffffff99, v14
	s_nop 0
	v_cndmask_b32_e32 v156, v235, v156, vcc
	v_cmp_gt_u32_e32 vcc, s88, v15
	v_add_u32_e32 v15, 0xffffff9a, v14
	v_add_u32_e32 v14, 0xffffff9b, v14
	v_cndmask_b32_e32 v157, v235, v157, vcc
	v_cmp_gt_u32_e32 vcc, s88, v15
	s_nop 1
	v_cndmask_b32_e32 v158, v235, v158, vcc
	v_cmp_gt_u32_e32 vcc, s88, v14
	s_nop 1
	v_cndmask_b32_e32 v159, v235, v159, vcc
.LBB0_334:
	v_max_f32_e32 v14, v144, v145
	v_max3_f32 v14, v14, v146, v147
	v_max3_f32 v14, v14, v148, v149
	v_max3_f32 v14, v14, v150, v151
	v_max3_f32 v14, v14, v152, v153
	v_max3_f32 v14, v14, v154, v155
	v_max3_f32 v14, v14, v156, v157
	v_max3_f32 v14, v14, v158, v159
	v_add_f32_e32 v14, v1, v14
	v_mov_b32_e32 v15, v14
	s_nop 1
	v_permlane32_swap_b32_e32 v14, v15
	v_max_f32_e32 v14, v14, v15
	v_add_f32_e32 v15, 0x41000000, v252
	v_cmp_gt_f32_e32 vcc, v14, v15
	s_cbranch_vccz .LBB0_336
	v_max_f32_e32 v14, v14, v14
	v_max_f32_e32 v15, v252, v252
	v_max_f32_e32 v15, v15, v14
	v_sub_f32_e32 v14, v252, v15
	v_exp_f32_e32 v14, v14
	v_mov_b32_e32 v252, v15
	v_pk_mul_f32 v[94:95], v[94:95], v[14:15] op_sel_hi:[1,0]
	v_pk_mul_f32 v[92:93], v[92:93], v[14:15] op_sel_hi:[1,0]
	v_pk_mul_f32 v[90:91], v[90:91], v[14:15] op_sel_hi:[1,0]
	v_pk_mul_f32 v[88:89], v[88:89], v[14:15] op_sel_hi:[1,0]
	v_pk_mul_f32 v[86:87], v[86:87], v[14:15] op_sel_hi:[1,0]
	v_pk_mul_f32 v[84:85], v[84:85], v[14:15] op_sel_hi:[1,0]
	v_pk_mul_f32 v[82:83], v[82:83], v[14:15] op_sel_hi:[1,0]
	v_pk_mul_f32 v[80:81], v[80:81], v[14:15] op_sel_hi:[1,0]
	v_pk_mul_f32 v[78:79], v[78:79], v[14:15] op_sel_hi:[1,0]
	v_pk_mul_f32 v[76:77], v[76:77], v[14:15] op_sel_hi:[1,0]
	v_pk_mul_f32 v[74:75], v[74:75], v[14:15] op_sel_hi:[1,0]
	v_pk_mul_f32 v[72:73], v[72:73], v[14:15] op_sel_hi:[1,0]
	v_pk_mul_f32 v[70:71], v[70:71], v[14:15] op_sel_hi:[1,0]
	v_pk_mul_f32 v[68:69], v[68:69], v[14:15] op_sel_hi:[1,0]
	v_pk_mul_f32 v[66:67], v[66:67], v[14:15] op_sel_hi:[1,0]
	v_pk_mul_f32 v[64:65], v[64:65], v[14:15] op_sel_hi:[1,0]
	v_mul_f32_e32 v253, v253, v14
.LBB0_336:
	v_sub_f32_e32 v14, v1, v252
	v_pk_add_f32 v[144:145], v[144:145], v[14:15] op_sel_hi:[1,0]
	v_pk_add_f32 v[146:147], v[146:147], v[14:15] op_sel_hi:[1,0]
	v_pk_add_f32 v[148:149], v[148:149], v[14:15] op_sel_hi:[1,0]
	v_pk_add_f32 v[150:151], v[150:151], v[14:15] op_sel_hi:[1,0]
	v_exp_f32_e32 v144, v144
	v_exp_f32_e32 v145, v145
	v_exp_f32_e32 v146, v146
	v_exp_f32_e32 v147, v147
	v_exp_f32_e32 v148, v148
	v_exp_f32_e32 v149, v149
	v_exp_f32_e32 v150, v150
	v_exp_f32_e32 v151, v151
	v_pk_add_f32 v[160:161], v[144:145], v[146:147]
	v_cvt_pk_bf16_f32 v144, v144, v145
	v_cvt_pk_bf16_f32 v145, v146, v147
	v_cvt_pk_bf16_f32 v146, v148, v149
	v_cvt_pk_bf16_f32 v147, v150, v151
	v_pk_add_f32 v[152:153], v[152:153], v[14:15] op_sel_hi:[1,0]
	v_pk_add_f32 v[154:155], v[154:155], v[14:15] op_sel_hi:[1,0]
	v_pk_add_f32 v[156:157], v[156:157], v[14:15] op_sel_hi:[1,0]
	s_nop 0
	v_exp_f32_e32 v152, v152
	s_waitcnt lgkmcnt(0)
	v_mfma_f32_32x32x16_bf16 v[80:95], v[208:211], v[144:147], v[80:95]
	v_exp_f32_e32 v153, v153
	v_exp_f32_e32 v154, v154
	v_exp_f32_e32 v155, v155
	v_exp_f32_e32 v156, v156
	v_exp_f32_e32 v157, v157
	v_mfma_f32_32x32x16_bf16 v[64:79], v[10:13], v[144:147], v[64:79]
	v_pk_add_f32 v[10:11], v[158:159], v[14:15] op_sel_hi:[1,0]
	v_cvt_pk_bf16_f32 v12, v156, v157
	v_exp_f32_e32 v14, v10
	v_exp_f32_e32 v15, v11
	v_cvt_pk_bf16_f32 v10, v152, v153
	v_cvt_pk_bf16_f32 v11, v154, v155
	v_cvt_pk_bf16_f32 v13, v14, v15
	s_nop 1
	v_mfma_f32_32x32x16_bf16 v[80:95], v[6:9], v[10:13], v[80:95]
	v_pk_add_f32 v[6:7], v[160:161], v[148:149]
	s_nop 0
	v_pk_add_f32 v[6:7], v[6:7], v[150:151]
	s_nop 0
	v_pk_add_f32 v[6:7], v[6:7], v[152:153]
	s_nop 0
	v_pk_add_f32 v[6:7], v[6:7], v[154:155]
	v_mfma_f32_32x32x16_bf16 v[64:79], v[2:5], v[10:13], v[64:79]
	v_pk_add_f32 v[6:7], v[6:7], v[156:157]
	s_nop 0
	v_pk_add_f32 v[6:7], v[6:7], v[14:15]
	s_nop 0
	v_add_f32_e32 v1, v6, v7
	v_add_f32_e32 v253, v253, v1
	s_branch .LBB0_338

; #define LAS __attribute__((address_space(3)))
;     ...
;             s16x4 vlo[2][2], vhi[2][2];
; #pragma unroll
;             for (int st = 0; st < 2; ++st) {
;                 vlo[0][st] = __builtin_bit_cast(s16x4, __builtin_amdgcn_ds_read_tr16_b64_v4i16((LAS s16x4*)(vb0 + 4096 * j + 2048 * st)));
;                 vhi[0][st] = __builtin_bit_cast(s16x4, __builtin_amdgcn_ds_read_tr16_b64_v4i16((LAS s16x4*)(vb0 + 4096 * j + 2048 * st + 1024)));
;                 vlo[1][st] = __builtin_bit_cast(s16x4, __builtin_amdgcn_ds_read_tr16_b64_v4i16((LAS s16x4*)(vb1 + 4096 * j + 2048 * st)));
;                 vhi[1][st] = __builtin_bit_cast(s16x4, __builtin_amdgcn_ds_read_tr16_b64_v4i16((LAS s16x4*)(vb1 + 4096 * j + 2048 * st + 1024))); }
;             f32x16 s; float cj;
;             const float cl = slope2 * (float)(32 * j - HALFW - ql);
;             if (j < JM) { s = __builtin_amdgcn_mfma_f32_32x32x16_bf16(kf[0], qf[0], CL, 0, 0, 0); cj = cl; }
;             else if (j == JM) { s = __builtin_amdgcn_mfma_f32_32x32x16_bf16(kf[0], qf[0], CM, 0, 0, 0); cj = 0.f; }
;             else { s = __builtin_amdgcn_mfma_f32_32x32x16_bf16(kf[0], qf[0], CR, 0, 0, 0); cj = -cl; }
.LBB0_345:
	s_andn2_b64 vcc, exec, s[76:77]
	s_cbranch_vccnz .LBB0_367
	s_waitcnt lgkmcnt(3)
	v_add_u32_e32 v1, v150, v242
	v_add_u32_e32 v4, v151, v242
	v_add_u32_e32 v1, 0x10000, v1
	v_add_u32_e32 v4, 0x10000, v4
	ds_read_b64_tr_b16 v[144:145], v1
	ds_read_b64_tr_b16 v[146:147], v1 offset:1024
	s_waitcnt lgkmcnt(3)
	ds_read_b64_tr_b16 v[10:11], v4
	ds_read_b64_tr_b16 v[12:13], v4 offset:1024
	ds_read_b64_tr_b16 v[6:7], v1 offset:2048
	ds_read_b64_tr_b16 v[8:9], v1 offset:3072
	v_add_u32_e32 v2, s91, v247
	v_cvt_f32_i32_e32 v15, v2
	ds_read_b64_tr_b16 v[2:3], v4 offset:2048
	ds_read_b64_tr_b16 v[4:5], v4 offset:3072
	s_cmp_gt_u32 s93, 1
	s_mov_b64 s[76:77], -1
	v_mul_f32_e32 v15, v230, v15
	s_cbranch_scc0 .LBB0_352
	s_cmp_lg_u32 s91, 64
	s_cbranch_scc0 .LBB0_349
	v_xor_b32_e32 v1, 0x80000000, v15
	s_mov_b64 s[76:77], 0
	s_waitcnt vmcnt(11)
	v_mfma_f32_32x32x16_bf16 v[96:111], v[140:143], v[176:179], v[32:47]
.LBB0_349:
	s_andn2_b64 vcc, exec, s[76:77]
	s_cbranch_vccnz .LBB0_351
	s_nop 9
	v_xor_b32_e32 v111, 0x80000000, v51
	v_xor_b32_e32 v110, 0x80000000, v50
	v_xor_b32_e32 v109, 0x80000000, v53
	v_xor_b32_e32 v108, 0x80000000, v52
	v_xor_b32_e32 v107, 0x80000000, v55
	v_xor_b32_e32 v106, 0x80000000, v54
	v_xor_b32_e32 v105, 0x80000000, v57
	v_xor_b32_e32 v104, 0x80000000, v56
	v_xor_b32_e32 v103, 0x80000000, v59
	v_xor_b32_e32 v102, 0x80000000, v58
	v_xor_b32_e32 v101, 0x80000000, v61
	v_xor_b32_e32 v100, 0x80000000, v60
	v_xor_b32_e32 v99, 0x80000000, v49
	v_xor_b32_e32 v98, 0x80000000, v48
	v_xor_b32_e32 v97, 0x80000000, v63
	v_xor_b32_e32 v96, 0x80000000, v62
	v_mov_b32_e32 v1, 0
	s_waitcnt vmcnt(11)
	v_mfma_f32_32x32x16_bf16 v[96:111], v[140:143], v[176:179], v[96:111]

; #define LAS __attribute__((address_space(3)))
;     ...
;             if (j < JM) { s = __builtin_amdgcn_mfma_f32_32x32x16_bf16(kf[0], qf[0], CL, 0, 0, 0); cj = cl; }
;             else if (j == JM) { s = __builtin_amdgcn_mfma_f32_32x32x16_bf16(kf[0], qf[0], CM, 0, 0, 0); cj = 0.f; }
;             else { s = __builtin_amdgcn_mfma_f32_32x32x16_bf16(kf[0], qf[0], CR, 0, 0, 0); cj = -cl; }
; #pragma unroll
;             for (int ks = 1; ks < 4; ++ks) s = __builtin_amdgcn_mfma_f32_32x32x16_bf16(kf[ks], qf[ks], s, 0, 0, 0);
; #pragma unroll
;             for (int ks = 0; ks < 4; ++ks) kf[ks] = *(const LAS bf16x8*)(kb + 4096 * jn + koff[ks]);
;             if (j == 0) {
; #pragma unroll
;                 for (int reg = 0; reg < 16; ++reg) s[reg] = ((reg & 3) + 8 * (reg >> 2) >= ql4) ? s[reg] : -INFINITY;
;             } else if (j == NTILE - 1) {
; #pragma unroll
;                 for (int reg = 0; reg < 16; ++reg) s[reg] = ((reg & 3) + 8 * (reg >> 2) <= ql4) ? s[reg] : -INFINITY;
.LBB0_352:
	s_andn2_b64 vcc, exec, s[76:77]
	s_cbranch_vccnz .LBB0_354
	s_waitcnt vmcnt(11)
	v_mfma_f32_32x32x16_bf16 v[96:111], v[140:143], v[176:179], v[16:31]
	v_mov_b32_e32 v1, v15
.LBB0_354:
	s_waitcnt vmcnt(10)
	v_mfma_f32_32x32x16_bf16 v[96:111], v[136:139], v[180:183], v[96:111]
	v_add_u32_e32 v15, v14, v237
	s_waitcnt lgkmcnt(8)
	v_add_u32_e32 v112, v14, v238
	ds_read_b128 v[140:143], v15
	ds_read_b128 v[136:139], v112
	v_add_u32_e32 v15, v14, v239
	v_add_u32_e32 v14, v14, v240
	s_cmp_lt_i32 s93, 4
	s_mov_b64 s[76:77], -1
	s_waitcnt vmcnt(9)
	v_mfma_f32_32x32x16_bf16 v[96:111], v[132:135], v[184:187], v[96:111]
	s_waitcnt vmcnt(8)
	v_mfma_f32_32x32x16_bf16 v[96:111], v[128:131], v[188:191], v[96:111]
	ds_read_b128 v[132:135], v15
	ds_read_b128 v[128:131], v14
	s_cbranch_scc1 .LBB0_358
	s_nop 8
	s_cmp_eq_u32 s93, 4
	s_cbranch_scc0 .LBB0_357
	v_cndmask_b32_e64 v96, v96, v235, s[6:7]
	v_cndmask_b32_e64 v97, v97, v235, s[8:9]
	v_cndmask_b32_e64 v98, v98, v235, s[10:11]
	v_cndmask_b32_e64 v99, v99, v235, s[12:13]
	v_cndmask_b32_e64 v100, v100, v235, s[14:15]
	v_cndmask_b32_e64 v101, v101, v235, s[16:17]
	v_cndmask_b32_e64 v102, v102, v235, s[18:19]
	v_cndmask_b32_e64 v103, v103, v235, s[20:21]
	v_cndmask_b32_e64 v104, v104, v235, s[22:23]
	v_cndmask_b32_e64 v105, v105, v235, s[24:25]
	v_cndmask_b32_e64 v106, v106, v235, s[26:27]
	v_cndmask_b32_e64 v107, v107, v235, s[28:29]
	v_cndmask_b32_e64 v108, v108, v235, s[30:31]
	v_cndmask_b32_e64 v109, v109, v235, s[34:35]
	v_cndmask_b32_e64 v110, v110, v235, s[36:37]
	v_cndmask_b32_e64 v111, v111, v235, s[38:39]

;     ...
;                 for (int reg = 0; reg < 16; ++reg) s[reg] = ((reg & 3) + 8 * (reg >> 2) >= ql4) ? s[reg] : -INFINITY;
;             } else if (j == NTILE - 1) {
; #pragma unroll
;                 for (int reg = 0; reg < 16; ++reg) s[reg] = ((reg & 3) + 8 * (reg >> 2) <= ql4) ? s[reg] : -INFINITY;
;             }
;             if (kt0 < 0 || kt0 + 31 >= Lsub) {
;                 const int kq = kt0 + 4 * hh;
; #pragma unroll
;                 for (int reg = 0; reg < 16; ++reg) { const int kpos = kq + (reg & 3) + 8 * (reg >> 2); s[reg] = ((unsigned)kpos < (unsigned)Lsub) ? s[reg] : -INFINITY; }
;             }
;             float tmax = fmaxf(fmaxf(s[0], s[1]), s[2]);
; #pragma unroll
;             for (int reg = 3; reg < 15; reg += 2) tmax = fmaxf(fmaxf(tmax, s[reg]), s[reg + 1]);
;             tmax = fmaxf(tmax, s[15]) + cj;
;             tmax = fmaxf(tmax, __shfl_xor(tmax, 32));
;             if (__any(tmax > m + 8.0f)) { const float mnew = fmaxf(m, tmax); const float alpha = __builtin_amdgcn_exp2f(m - mnew); lsum *= alpha; m = mnew;
; #pragma unroll
;                 for (int reg = 0; reg < 16; ++reg) { o0[reg] *= alpha; o1[reg] *= alpha; } }
;             const float dd = cj - m;
;             f32x2 ps2 = {0.f, 0.f}; const f32x2 dd2 = {dd, dd};
; #pragma unroll
;             for (int rp = 0; rp < 8; ++rp) { f32x2 t; { const f32x2 in_ = {s[2 * rp], s[2 * rp + 1]}; asm("v_pk_add_f32 %0, %1, %2" : "=v"(t) : "v"(in_), "v"(dd2)); } t[0] = __builtin_amdgcn_exp2f(t[0]); t[1] = __builtin_amdgcn_exp2f(t[1]); s[2 * rp] = t[0]; s[2 * rp + 1] = t[1]; asm("v_pk_add_f32 %0, %1, %2" : "=v"(ps2) : "v"(ps2), "v"(t)); }
;             lsum += ps2[0] + ps2[1];
;             bf16x8 pf[2];
; #pragma unroll
;             for (int st = 0; st < 2; ++st) { v4u t; t.x = pk2(s[8 * st + 0], s[8 * st + 1]); t.y = pk2(s[8 * st + 2], s[8 * st + 3]); t.z = pk2(s[8 * st + 4], s[8 * st + 5]); t.w = pk2(s[8 * st + 6], s[8 * st + 7]); pf[st] = __builtin_bit_cast(bf16x8, t); }
; #pragma unroll
;             for (int st = 0; st < 2; ++st) {
;                 const bf16x8 v0 = (bf16x8){vlo[0][st][0], vlo[0][st][1], vlo[0][st][2], vlo[0][st][3], vhi[0][st][0], vhi[0][st][1], vhi[0][st][2], vhi[0][st][3]};
;                 const bf16x8 v1 = (bf16x8){vlo[1][st][0], vlo[1][st][1], vlo[1][st][2], vlo[1][st][3], vhi[1][st][0], vhi[1][st][1], vhi[1][st][2], vhi[1][st][3]};
.LBB0_358:
	s_andn2_b64 vcc, exec, s[76:77]
	s_cbranch_vccnz .LBB0_362
	s_cmp_eq_u32 s93, 0
	s_cbranch_scc0 .LBB0_361
	s_nop 4
	v_cndmask_b32_e64 v96, v96, v235, s[96:97]
	v_cndmask_b32_e64 v97, v97, v235, s[44:45]
	v_cndmask_b32_e64 v98, v98, v235, s[46:47]
	v_cndmask_b32_e64 v99, v99, v235, s[82:83]
	v_cndmask_b32_e64 v100, v100, v235, s[84:85]
	v_cndmask_b32_e64 v101, v101, v235, s[78:79]
	v_cndmask_b32_e64 v102, v102, v235, s[86:87]
	v_cndmask_b32_e64 v103, v103, v235, s[0:1]
	v_cndmask_b32_e64 v104, v104, v235, s[56:57]
	v_cndmask_b32_e64 v105, v105, v235, s[58:59]
	v_cndmask_b32_e64 v106, v106, v235, s[60:61]
	v_cndmask_b32_e64 v107, v107, v235, s[62:63]
	v_cndmask_b32_e64 v108, v108, v235, s[64:65]
	v_cndmask_b32_e64 v109, v109, v235, s[66:67]
	v_cndmask_b32_e64 v110, v110, v235, s[68:69]
	v_cndmask_b32_e64 v111, v111, v235, s[70:71]
.LBB0_361:
	s_nop 4
.LBB0_362:
	s_sub_i32 s74, s72, 33
	s_cmp_gt_i32 s73, -1
	s_cselect_b64 s[72:73], -1, 0
	s_cmp_lt_i32 s74, s88
	s_cselect_b64 s[74:75], -1, 0
	s_and_b64 s[72:73], s[72:73], s[74:75]
	s_and_b64 vcc, exec, s[72:73]
	s_cbranch_vccnz .LBB0_364
	v_add_u32_e32 v14, s91, v246
	v_subrev_u32_e32 v15, 64, v14
	v_cmp_gt_u32_e32 vcc, s88, v15
	v_subrev_u32_e32 v15, 63, v14
	s_nop 0
	v_cndmask_b32_e32 v96, v235, v96, vcc
	v_cmp_gt_u32_e32 vcc, s88, v15
	v_subrev_u32_e32 v15, 62, v14
	s_nop 0
	v_cndmask_b32_e32 v97, v235, v97, vcc
	v_cmp_gt_u32_e32 vcc, s88, v15
	v_subrev_u32_e32 v15, 61, v14
	s_nop 0
	v_cndmask_b32_e32 v98, v235, v98, vcc
	v_cmp_gt_u32_e32 vcc, s88, v15
	v_subrev_u32_e32 v15, 56, v14
	s_nop 0
	v_cndmask_b32_e32 v99, v235, v99, vcc
	v_cmp_gt_u32_e32 vcc, s88, v15
	v_subrev_u32_e32 v15, 55, v14
	s_nop 0
	v_cndmask_b32_e32 v100, v235, v100, vcc
	v_cmp_gt_u32_e32 vcc, s88, v15
	v_subrev_u32_e32 v15, 54, v14
	s_nop 0
	v_cndmask_b32_e32 v101, v235, v101, vcc
	v_cmp_gt_u32_e32 vcc, s88, v15
	v_subrev_u32_e32 v15, 53, v14
	s_nop 0
	v_cndmask_b32_e32 v102, v235, v102, vcc
	v_cmp_gt_u32_e32 vcc, s88, v15
	v_subrev_u32_e32 v15, 48, v14
	s_nop 0
	v_cndmask_b32_e32 v103, v235, v103, vcc
	v_cmp_gt_u32_e32 vcc, s88, v15
	v_subrev_u32_e32 v15, 47, v14
	s_nop 0
	v_cndmask_b32_e32 v104, v235, v104, vcc
	v_cmp_gt_u32_e32 vcc, s88, v15
	v_subrev_u32_e32 v15, 46, v14
	s_nop 0
	v_cndmask_b32_e32 v105, v235, v105, vcc
	v_cmp_gt_u32_e32 vcc, s88, v15
	v_subrev_u32_e32 v15, 45, v14
	s_nop 0
	v_cndmask_b32_e32 v106, v235, v106, vcc
	v_cmp_gt_u32_e32 vcc, s88, v15
	v_subrev_u32_e32 v15, 40, v14
	s_nop 0
	v_cndmask_b32_e32 v107, v235, v107, vcc
	v_cmp_gt_u32_e32 vcc, s88, v15
	v_subrev_u32_e32 v15, 39, v14
	s_nop 0
	v_cndmask_b32_e32 v108, v235, v108, vcc
	v_cmp_gt_u32_e32 vcc, s88, v15
	v_subrev_u32_e32 v15, 38, v14
	v_subrev_u32_e32 v14, 37, v14
	v_cndmask_b32_e32 v109, v235, v109, vcc
	v_cmp_gt_u32_e32 vcc, s88, v15
	s_nop 1
	v_cndmask_b32_e32 v110, v235, v110, vcc
	v_cmp_gt_u32_e32 vcc, s88, v14
	s_nop 1
	v_cndmask_b32_e32 v111, v235, v111, vcc
.LBB0_364:
	v_max_f32_e32 v14, v96, v97
	v_max3_f32 v14, v14, v98, v99
	v_max3_f32 v14, v14, v100, v101
	v_max3_f32 v14, v14, v102, v103
	v_max3_f32 v14, v14, v104, v105
	v_max3_f32 v14, v14, v106, v107
	v_max3_f32 v14, v14, v108, v109
	v_max3_f32 v14, v14, v110, v111
	v_add_f32_e32 v14, v1, v14
	v_mov_b32_e32 v15, v14
	s_nop 1
	v_permlane32_swap_b32_e32 v14, v15
	v_max_f32_e32 v14, v14, v15
	v_add_f32_e32 v15, 0x41000000, v148
	v_cmp_gt_f32_e32 vcc, v14, v15
	s_cbranch_vccz .LBB0_366
	v_max_f32_e32 v14, v14, v14
	v_max_f32_e32 v15, v148, v148
	v_max_f32_e32 v15, v15, v14
	v_sub_f32_e32 v14, v148, v15
	v_exp_f32_e32 v14, v14
	v_mov_b32_e32 v148, v15
	v_pk_mul_f32 v[94:95], v[94:95], v[14:15] op_sel_hi:[1,0]
	v_pk_mul_f32 v[92:93], v[92:93], v[14:15] op_sel_hi:[1,0]
	v_pk_mul_f32 v[90:91], v[90:91], v[14:15] op_sel_hi:[1,0]
	v_pk_mul_f32 v[88:89], v[88:89], v[14:15] op_sel_hi:[1,0]
	v_pk_mul_f32 v[86:87], v[86:87], v[14:15] op_sel_hi:[1,0]
	v_pk_mul_f32 v[84:85], v[84:85], v[14:15] op_sel_hi:[1,0]
	v_pk_mul_f32 v[82:83], v[82:83], v[14:15] op_sel_hi:[1,0]
	v_pk_mul_f32 v[80:81], v[80:81], v[14:15] op_sel_hi:[1,0]
	v_pk_mul_f32 v[78:79], v[78:79], v[14:15] op_sel_hi:[1,0]
	v_pk_mul_f32 v[76:77], v[76:77], v[14:15] op_sel_hi:[1,0]
	v_pk_mul_f32 v[74:75], v[74:75], v[14:15] op_sel_hi:[1,0]
	v_pk_mul_f32 v[72:73], v[72:73], v[14:15] op_sel_hi:[1,0]
	v_pk_mul_f32 v[70:71], v[70:71], v[14:15] op_sel_hi:[1,0]
	v_pk_mul_f32 v[68:69], v[68:69], v[14:15] op_sel_hi:[1,0]
	v_pk_mul_f32 v[66:67], v[66:67], v[14:15] op_sel_hi:[1,0]
	v_pk_mul_f32 v[64:65], v[64:65], v[14:15] op_sel_hi:[1,0]
	v_mul_f32_e32 v149, v149, v14
.LBB0_366:
	v_sub_f32_e32 v14, v1, v148
	v_pk_add_f32 v[96:97], v[96:97], v[14:15] op_sel_hi:[1,0]
	v_pk_add_f32 v[98:99], v[98:99], v[14:15] op_sel_hi:[1,0]
	v_pk_add_f32 v[100:101], v[100:101], v[14:15] op_sel_hi:[1,0]
	v_pk_add_f32 v[102:103], v[102:103], v[14:15] op_sel_hi:[1,0]
	v_exp_f32_e32 v96, v96
	v_exp_f32_e32 v97, v97
	v_exp_f32_e32 v98, v98
	v_exp_f32_e32 v99, v99
	v_exp_f32_e32 v100, v100
	v_exp_f32_e32 v101, v101
	v_exp_f32_e32 v102, v102
	v_exp_f32_e32 v103, v103
	v_pk_add_f32 v[112:113], v[96:97], v[98:99]
	v_cvt_pk_bf16_f32 v96, v96, v97
	v_cvt_pk_bf16_f32 v97, v98, v99
	v_cvt_pk_bf16_f32 v98, v100, v101
	v_cvt_pk_bf16_f32 v99, v102, v103
	v_pk_add_f32 v[104:105], v[104:105], v[14:15] op_sel_hi:[1,0]
	v_pk_add_f32 v[106:107], v[106:107], v[14:15] op_sel_hi:[1,0]
	v_pk_add_f32 v[108:109], v[108:109], v[14:15] op_sel_hi:[1,0]
	s_nop 0
	v_exp_f32_e32 v104, v104
	s_waitcnt lgkmcnt(0)
	v_mfma_f32_32x32x16_bf16 v[80:95], v[144:147], v[96:99], v[80:95]
	v_exp_f32_e32 v105, v105
	v_exp_f32_e32 v106, v106
	v_exp_f32_e32 v107, v107
	v_exp_f32_e32 v108, v108
	v_exp_f32_e32 v109, v109
	v_mfma_f32_32x32x16_bf16 v[64:79], v[10:13], v[96:99], v[64:79]
	v_pk_add_f32 v[10:11], v[110:111], v[14:15] op_sel_hi:[1,0]
	v_cvt_pk_bf16_f32 v12, v108, v109
	v_exp_f32_e32 v14, v10
	v_exp_f32_e32 v15, v11
	v_cvt_pk_bf16_f32 v10, v104, v105
	v_cvt_pk_bf16_f32 v11, v106, v107
	v_cvt_pk_bf16_f32 v13, v14, v15
	s_nop 1
	v_mfma_f32_32x32x16_bf16 v[80:95], v[6:9], v[10:13], v[80:95]
	v_pk_add_f32 v[6:7], v[112:113], v[100:101]
	s_nop 0
	v_pk_add_f32 v[6:7], v[6:7], v[102:103]
	s_nop 0
	v_pk_add_f32 v[6:7], v[6:7], v[104:105]
	s_nop 0
	v_pk_add_f32 v[6:7], v[6:7], v[106:107]
	v_mfma_f32_32x32x16_bf16 v[64:79], v[2:5], v[10:13], v[64:79]
	v_pk_add_f32 v[6:7], v[6:7], v[108:109]
	s_nop 0
	v_pk_add_f32 v[6:7], v[6:7], v[14:15]
	s_nop 0
	v_add_f32_e32 v1, v6, v7
	v_add_f32_e32 v149, v149, v1
	s_branch .LBB0_368
